# v050 + LDS-DMA stage groups issued in front of each load segment's ds_read group (dependency-checked hoist) in all four K-loops
# speedup vs baseline: 1.0003x; 1.0001x over previous
.LBB0_270:
	s_add_u32 s34, s8, 0xfff80080
	s_addc_u32 s35, s9, -1
	s_and_b64 s[30:31], s[30:31], exec
	s_cselect_b32 s35, s2, s35
	s_cselect_b32 s34, s25, s34
	s_cselect_b32 s31, s23, s55
	s_cselect_b32 s30, s54, s1
	s_add_i32 s57, 0, 0x10000
	s_add_i32 s62, 0, 0x14000
	v_add_u32_e32 v72, s57, v181
	ds_read_b128 v[68:71], v72
	ds_read_b128 v[82:85], v72 offset:1024
	ds_read_b128 v[86:89], v72 offset:2048
	ds_read_b128 v[146:149], v72 offset:3072
	v_add_u32_e32 v72, s62, v181
	ds_read_b128 v[150:153], v72
	ds_read_b128 v[154:157], v72 offset:1024
	ds_read_b128 v[158:161], v72 offset:2048
	ds_read_b128 v[202:205], v72 offset:3072
	v_lshl_add_u64 v[72:73], s[8:9], 0, v[172:173]
	s_add_i32 m0, s41, 0xc000
	s_nop 0
	global_load_lds_dwordx4 v[72:73], off
	v_lshl_add_u64 v[72:73], s[8:9], 0, v[170:171]
	s_add_i32 m0, s41, 0xe000
	s_nop 0
	global_load_lds_dwordx4 v[72:73], off
	ds_read_b128 v[206:209], v199
	ds_read_b128 v[210:213], v199 offset:1024
	ds_read_b128 v[214:217], v199 offset:2048
	ds_read_b128 v[226:229], v199 offset:3072
	ds_read_b128 v[230:233], v199 offset:4096
	ds_read_b128 v[234:237], v199 offset:5120
	ds_read_b128 v[238:241], v199 offset:6144
	ds_read_b128 v[242:245], v199 offset:7168
	s_waitcnt vmcnt(8)
	s_waitcnt lgkmcnt(0)
	s_barrier
	s_setprio 1
	v_mfma_f32_16x16x32_bf16 v[142:145], v[68:71], v[206:209], v[142:145]
	v_mfma_f32_16x16x32_bf16 v[138:141], v[86:89], v[206:209], v[138:141]
	v_mfma_f32_16x16x32_bf16 v[126:129], v[68:71], v[214:217], v[126:129]
	v_mfma_f32_16x16x32_bf16 v[122:125], v[86:89], v[214:217], v[122:125]
	v_mfma_f32_16x16x32_bf16 v[110:113], v[68:71], v[230:233], v[110:113]
	v_mfma_f32_16x16x32_bf16 v[106:109], v[86:89], v[230:233], v[106:109]
	v_mfma_f32_16x16x32_bf16 v[94:97], v[68:71], v[238:241], v[94:97]
	v_mfma_f32_16x16x32_bf16 v[90:93], v[86:89], v[238:241], v[90:93]
	v_mfma_f32_16x16x32_bf16 v[142:145], v[82:85], v[210:213], v[142:145]
	v_mfma_f32_16x16x32_bf16 v[138:141], v[146:149], v[210:213], v[138:141]
	v_mfma_f32_16x16x32_bf16 v[126:129], v[82:85], v[226:229], v[126:129]
	v_mfma_f32_16x16x32_bf16 v[122:125], v[146:149], v[226:229], v[122:125]
	v_mfma_f32_16x16x32_bf16 v[110:113], v[82:85], v[234:237], v[110:113]
	v_mfma_f32_16x16x32_bf16 v[106:109], v[146:149], v[234:237], v[106:109]
	v_mfma_f32_16x16x32_bf16 v[94:97], v[82:85], v[242:245], v[94:97]
	v_mfma_f32_16x16x32_bf16 v[90:93], v[146:149], v[242:245], v[90:93]
	v_mfma_f32_16x16x32_bf16 v[134:137], v[150:153], v[206:209], v[134:137]
	v_mfma_f32_16x16x32_bf16 v[130:133], v[158:161], v[206:209], v[130:133]
	v_mfma_f32_16x16x32_bf16 v[118:121], v[150:153], v[214:217], v[118:121]
	v_mfma_f32_16x16x32_bf16 v[114:117], v[158:161], v[214:217], v[114:117]
	v_mfma_f32_16x16x32_bf16 v[102:105], v[150:153], v[230:233], v[102:105]
	v_mfma_f32_16x16x32_bf16 v[98:101], v[158:161], v[230:233], v[98:101]
	v_mfma_f32_16x16x32_bf16 v[78:81], v[150:153], v[238:241], v[78:81]
	v_mfma_f32_16x16x32_bf16 v[72:75], v[158:161], v[238:241], v[74:77]
	v_mfma_f32_16x16x32_bf16 v[134:137], v[154:157], v[210:213], v[134:137]
	v_mfma_f32_16x16x32_bf16 v[130:133], v[202:205], v[210:213], v[130:133]
	v_mfma_f32_16x16x32_bf16 v[118:121], v[154:157], v[226:229], v[118:121]
	v_mfma_f32_16x16x32_bf16 v[114:117], v[202:205], v[226:229], v[114:117]
	v_mfma_f32_16x16x32_bf16 v[102:105], v[154:157], v[234:237], v[102:105]
	v_mfma_f32_16x16x32_bf16 v[98:101], v[202:205], v[234:237], v[98:101]
	v_mfma_f32_16x16x32_bf16 v[78:81], v[154:157], v[242:245], v[78:81]
	v_mfma_f32_16x16x32_bf16 v[72:75], v[202:205], v[242:245], v[72:75]
	s_setprio 0
	s_barrier
	s_add_i32 s57, s57, s40
	v_lshl_add_u64 v[178:179], s[30:31], 0, v[0:1]
	s_mov_b32 m0, s57
	s_nop 0
	global_load_lds_dwordx4 v[178:179], off
	s_add_i32 m0, s57, 0x2000
	s_add_u32 s60, s30, 0x80000
	v_lshl_add_u64 v[250:251], s[30:31], 0, v[162:163]
	s_addc_u32 s61, s31, 0
	s_add_i32 s57, s62, s40
	global_load_lds_dwordx4 v[250:251], off
	v_lshl_add_u64 v[76:77], s[60:61], 0, v[0:1]
	s_mov_b32 m0, s57
	v_lshl_add_u64 v[252:253], s[34:35], 0, v[166:167]
	global_load_lds_dwordx4 v[76:77], off
	v_lshl_add_u64 v[76:77], s[60:61], 0, v[162:163]
	s_add_i32 m0, s57, 0x2000
	v_lshl_add_u64 v[220:221], s[34:35], 0, v[164:165]
	global_load_lds_dwordx4 v[76:77], off
	s_mov_b32 m0, s41
	s_nop 0
	global_load_lds_dwordx4 v[252:253], off
	s_mov_b32 m0, s42
	s_nop 0
	global_load_lds_dwordx4 v[220:221], off
	ds_read_b128 v[206:209], v199 offset:16384
	ds_read_b128 v[210:213], v199 offset:17408
	ds_read_b128 v[214:217], v199 offset:18432
	ds_read_b128 v[226:229], v199 offset:19456
	ds_read_b128 v[230:233], v199 offset:20480
	ds_read_b128 v[234:237], v199 offset:21504
	ds_read_b128 v[238:241], v199 offset:22528
	ds_read_b128 v[242:245], v199 offset:23552
	s_waitcnt vmcnt(8)
	s_waitcnt lgkmcnt(0)
	s_barrier
	s_setprio 1
	v_mfma_f32_16x16x32_bf16 v[62:65], v[68:71], v[206:209], v[62:65]
	v_mfma_f32_16x16x32_bf16 v[58:61], v[86:89], v[206:209], v[58:61]
	v_mfma_f32_16x16x32_bf16 v[46:49], v[68:71], v[214:217], v[46:49]
	v_mfma_f32_16x16x32_bf16 v[42:45], v[86:89], v[214:217], v[42:45]
	v_mfma_f32_16x16x32_bf16 v[30:33], v[68:71], v[230:233], v[30:33]
	v_mfma_f32_16x16x32_bf16 v[26:29], v[86:89], v[230:233], v[26:29]
	v_mfma_f32_16x16x32_bf16 v[14:17], v[68:71], v[238:241], v[14:17]
	v_mfma_f32_16x16x32_bf16 v[10:13], v[86:89], v[238:241], v[10:13]
	v_mfma_f32_16x16x32_bf16 v[62:65], v[82:85], v[210:213], v[62:65]
	v_mfma_f32_16x16x32_bf16 v[58:61], v[146:149], v[210:213], v[58:61]
	v_mfma_f32_16x16x32_bf16 v[46:49], v[82:85], v[226:229], v[46:49]
	v_mfma_f32_16x16x32_bf16 v[42:45], v[146:149], v[226:229], v[42:45]
	v_mfma_f32_16x16x32_bf16 v[30:33], v[82:85], v[234:237], v[30:33]
	v_mfma_f32_16x16x32_bf16 v[26:29], v[146:149], v[234:237], v[26:29]
	v_mfma_f32_16x16x32_bf16 v[14:17], v[82:85], v[242:245], v[14:17]
	v_mfma_f32_16x16x32_bf16 v[10:13], v[146:149], v[242:245], v[10:13]
	v_mfma_f32_16x16x32_bf16 v[54:57], v[150:153], v[206:209], v[54:57]
	v_mfma_f32_16x16x32_bf16 v[50:53], v[158:161], v[206:209], v[50:53]
	v_mfma_f32_16x16x32_bf16 v[38:41], v[150:153], v[214:217], v[38:41]
	v_mfma_f32_16x16x32_bf16 v[34:37], v[158:161], v[214:217], v[34:37]
	v_mfma_f32_16x16x32_bf16 v[22:25], v[150:153], v[230:233], v[22:25]
	v_mfma_f32_16x16x32_bf16 v[18:21], v[158:161], v[230:233], v[18:21]
	v_mfma_f32_16x16x32_bf16 v[6:9], v[150:153], v[238:241], v[6:9]
	v_mfma_f32_16x16x32_bf16 v[2:5], v[158:161], v[238:241], v[2:5]
	v_mfma_f32_16x16x32_bf16 v[54:57], v[154:157], v[210:213], v[54:57]
	v_mfma_f32_16x16x32_bf16 v[50:53], v[202:205], v[210:213], v[50:53]
	v_mfma_f32_16x16x32_bf16 v[38:41], v[154:157], v[226:229], v[38:41]
	v_mfma_f32_16x16x32_bf16 v[34:37], v[202:205], v[226:229], v[34:37]
	v_mfma_f32_16x16x32_bf16 v[22:25], v[154:157], v[234:237], v[22:25]
	v_mfma_f32_16x16x32_bf16 v[18:21], v[202:205], v[234:237], v[18:21]
	v_mfma_f32_16x16x32_bf16 v[6:9], v[154:157], v[242:245], v[6:9]
	v_mfma_f32_16x16x32_bf16 v[2:5], v[202:205], v[242:245], v[2:5]
	s_setprio 0
	s_barrier
	s_add_i32 s57, 0, 0x18000
	s_add_i32 s60, 0, 0x1c000
	s_add_u32 s34, s34, 0x80000
	s_addc_u32 s35, s35, 0
	s_mov_b32 m0, s43
	v_add_u32_e32 v76, s57, v181
	ds_read_b128 v[68:71], v76
	ds_read_b128 v[82:85], v76 offset:1024
	ds_read_b128 v[86:89], v76 offset:2048
	ds_read_b128 v[146:149], v76 offset:3072
	v_add_u32_e32 v76, s60, v181
	ds_read_b128 v[150:153], v76
	ds_read_b128 v[154:157], v76 offset:1024
	ds_read_b128 v[158:161], v76 offset:2048
	ds_read_b128 v[202:205], v76 offset:3072
	v_lshl_add_u64 v[76:77], s[34:35], 0, v[166:167]
	global_load_lds_dwordx4 v[76:77], off
	v_lshl_add_u64 v[76:77], s[34:35], 0, v[164:165]
	s_mov_b32 m0, s44
	s_nop 0
	global_load_lds_dwordx4 v[76:77], off
	ds_read_b128 v[206:209], v199 offset:32768
	ds_read_b128 v[210:213], v199 offset:33792
	ds_read_b128 v[214:217], v199 offset:34816
	ds_read_b128 v[226:229], v199 offset:35840
	ds_read_b128 v[230:233], v199 offset:36864
	ds_read_b128 v[234:237], v199 offset:37888
	ds_read_b128 v[238:241], v199 offset:38912
	ds_read_b128 v[242:245], v199 offset:39936
	s_waitcnt vmcnt(8)
	s_waitcnt lgkmcnt(0)
	s_barrier
	s_setprio 1
	v_mfma_f32_16x16x32_bf16 v[142:145], v[68:71], v[206:209], v[142:145]
	v_mfma_f32_16x16x32_bf16 v[138:141], v[86:89], v[206:209], v[138:141]
	v_mfma_f32_16x16x32_bf16 v[126:129], v[68:71], v[214:217], v[126:129]
	v_mfma_f32_16x16x32_bf16 v[122:125], v[86:89], v[214:217], v[122:125]
	v_mfma_f32_16x16x32_bf16 v[110:113], v[68:71], v[230:233], v[110:113]
	v_mfma_f32_16x16x32_bf16 v[106:109], v[86:89], v[230:233], v[106:109]
	v_mfma_f32_16x16x32_bf16 v[94:97], v[68:71], v[238:241], v[94:97]
	v_mfma_f32_16x16x32_bf16 v[90:93], v[86:89], v[238:241], v[90:93]
	v_mfma_f32_16x16x32_bf16 v[142:145], v[82:85], v[210:213], v[142:145]
	v_mfma_f32_16x16x32_bf16 v[138:141], v[146:149], v[210:213], v[138:141]
	v_mfma_f32_16x16x32_bf16 v[126:129], v[82:85], v[226:229], v[126:129]
	v_mfma_f32_16x16x32_bf16 v[122:125], v[146:149], v[226:229], v[122:125]
	v_mfma_f32_16x16x32_bf16 v[110:113], v[82:85], v[234:237], v[110:113]
	v_mfma_f32_16x16x32_bf16 v[106:109], v[146:149], v[234:237], v[106:109]
	v_mfma_f32_16x16x32_bf16 v[94:97], v[82:85], v[242:245], v[94:97]
	v_mfma_f32_16x16x32_bf16 v[90:93], v[146:149], v[242:245], v[90:93]
	v_mfma_f32_16x16x32_bf16 v[134:137], v[150:153], v[206:209], v[134:137]
	v_mfma_f32_16x16x32_bf16 v[130:133], v[158:161], v[206:209], v[130:133]
	v_mfma_f32_16x16x32_bf16 v[118:121], v[150:153], v[214:217], v[118:121]
	v_mfma_f32_16x16x32_bf16 v[114:117], v[158:161], v[214:217], v[114:117]
	v_mfma_f32_16x16x32_bf16 v[102:105], v[150:153], v[230:233], v[102:105]
	v_mfma_f32_16x16x32_bf16 v[98:101], v[158:161], v[230:233], v[98:101]
	v_mfma_f32_16x16x32_bf16 v[76:79], v[150:153], v[238:241], v[78:81]
	v_mfma_f32_16x16x32_bf16 v[72:75], v[158:161], v[238:241], v[72:75]
	v_mfma_f32_16x16x32_bf16 v[134:137], v[154:157], v[210:213], v[134:137]
	v_mfma_f32_16x16x32_bf16 v[130:133], v[202:205], v[210:213], v[130:133]
	v_mfma_f32_16x16x32_bf16 v[118:121], v[154:157], v[226:229], v[118:121]
	v_mfma_f32_16x16x32_bf16 v[114:117], v[202:205], v[226:229], v[114:117]
	v_mfma_f32_16x16x32_bf16 v[102:105], v[154:157], v[234:237], v[102:105]
	v_mfma_f32_16x16x32_bf16 v[98:101], v[202:205], v[234:237], v[98:101]
	v_mfma_f32_16x16x32_bf16 v[78:81], v[154:157], v[242:245], v[76:79]
	v_mfma_f32_16x16x32_bf16 v[74:77], v[202:205], v[242:245], v[72:75]
	s_setprio 0
	s_barrier
	s_add_i32 s34, s57, s40
	v_lshl_add_u64 v[72:73], v[178:179], 0, s[96:97]
	s_mov_b32 m0, s34
	s_nop 0
	global_load_lds_dwordx4 v[72:73], off
	s_add_i32 m0, s34, 0x2000
	s_add_u32 s30, s30, 0x80080
	v_lshl_add_u64 v[72:73], v[250:251], 0, s[96:97]
	s_addc_u32 s31, s31, 0
	s_add_i32 s34, s60, s40
	global_load_lds_dwordx4 v[72:73], off
	v_lshl_add_u64 v[72:73], s[30:31], 0, v[0:1]
	s_mov_b32 m0, s34
	s_nop 0
	global_load_lds_dwordx4 v[72:73], off
	v_lshl_add_u64 v[72:73], s[30:31], 0, v[162:163]
	s_add_i32 m0, s34, 0x2000
	s_nop 0
	global_load_lds_dwordx4 v[72:73], off
	v_lshl_add_u64 v[72:73], v[252:253], 0, s[96:97]
	s_mov_b32 m0, s47
	s_nop 0
	global_load_lds_dwordx4 v[72:73], off
	v_lshl_add_u64 v[72:73], v[220:221], 0, s[96:97]
	s_mov_b32 m0, s50
	s_nop 0
	global_load_lds_dwordx4 v[72:73], off
	ds_read_b128 v[206:209], v199 offset:49152
	ds_read_b128 v[210:213], v199 offset:50176
	ds_read_b128 v[214:217], v199 offset:51200
	ds_read_b128 v[226:229], v199 offset:52224
	ds_read_b128 v[230:233], v199 offset:53248
	ds_read_b128 v[234:237], v199 offset:54272
	ds_read_b128 v[238:241], v199 offset:55296
	ds_read_b128 v[242:245], v199 offset:56320
	s_waitcnt vmcnt(8)
	s_waitcnt lgkmcnt(0)
	s_barrier
	s_setprio 1
	v_mfma_f32_16x16x32_bf16 v[62:65], v[68:71], v[206:209], v[62:65]
	v_mfma_f32_16x16x32_bf16 v[58:61], v[86:89], v[206:209], v[58:61]
	v_mfma_f32_16x16x32_bf16 v[46:49], v[68:71], v[214:217], v[46:49]
	v_mfma_f32_16x16x32_bf16 v[42:45], v[86:89], v[214:217], v[42:45]
	v_mfma_f32_16x16x32_bf16 v[30:33], v[68:71], v[230:233], v[30:33]
	v_mfma_f32_16x16x32_bf16 v[26:29], v[86:89], v[230:233], v[26:29]
	v_mfma_f32_16x16x32_bf16 v[14:17], v[68:71], v[238:241], v[14:17]
	v_mfma_f32_16x16x32_bf16 v[10:13], v[86:89], v[238:241], v[10:13]
	v_mfma_f32_16x16x32_bf16 v[62:65], v[82:85], v[210:213], v[62:65]
	v_mfma_f32_16x16x32_bf16 v[58:61], v[146:149], v[210:213], v[58:61]
	v_mfma_f32_16x16x32_bf16 v[46:49], v[82:85], v[226:229], v[46:49]
	v_mfma_f32_16x16x32_bf16 v[42:45], v[146:149], v[226:229], v[42:45]
	v_mfma_f32_16x16x32_bf16 v[30:33], v[82:85], v[234:237], v[30:33]
	v_mfma_f32_16x16x32_bf16 v[26:29], v[146:149], v[234:237], v[26:29]
	v_mfma_f32_16x16x32_bf16 v[14:17], v[82:85], v[242:245], v[14:17]
	v_mfma_f32_16x16x32_bf16 v[10:13], v[146:149], v[242:245], v[10:13]
	v_mfma_f32_16x16x32_bf16 v[54:57], v[150:153], v[206:209], v[54:57]
	v_mfma_f32_16x16x32_bf16 v[50:53], v[158:161], v[206:209], v[50:53]
	v_mfma_f32_16x16x32_bf16 v[38:41], v[150:153], v[214:217], v[38:41]
	v_mfma_f32_16x16x32_bf16 v[34:37], v[158:161], v[214:217], v[34:37]
	v_mfma_f32_16x16x32_bf16 v[22:25], v[150:153], v[230:233], v[22:25]
	v_mfma_f32_16x16x32_bf16 v[18:21], v[158:161], v[230:233], v[18:21]
	v_mfma_f32_16x16x32_bf16 v[6:9], v[150:153], v[238:241], v[6:9]
	v_mfma_f32_16x16x32_bf16 v[2:5], v[158:161], v[238:241], v[2:5]
	v_mfma_f32_16x16x32_bf16 v[54:57], v[154:157], v[210:213], v[54:57]
	v_mfma_f32_16x16x32_bf16 v[50:53], v[202:205], v[210:213], v[50:53]
	v_mfma_f32_16x16x32_bf16 v[38:41], v[154:157], v[226:229], v[38:41]
	v_mfma_f32_16x16x32_bf16 v[34:37], v[202:205], v[226:229], v[34:37]
	v_mfma_f32_16x16x32_bf16 v[22:25], v[154:157], v[234:237], v[22:25]
	v_mfma_f32_16x16x32_bf16 v[18:21], v[202:205], v[234:237], v[18:21]
	v_mfma_f32_16x16x32_bf16 v[6:9], v[154:157], v[242:245], v[6:9]
	v_mfma_f32_16x16x32_bf16 v[2:5], v[202:205], v[242:245], v[2:5]
	s_setprio 0
	s_barrier
	s_add_i32 s56, s56, 2
	s_add_u32 s1, s1, 0x100
	s_addc_u32 s55, s55, 0
	s_add_u32 s8, s8, 0x100
	s_addc_u32 s9, s9, 0
	s_cmp_gt_u32 s56, 29
	s_cbranch_scc1 .LBB0_273

.LBB0_617:
	s_add_u32 s34, s8, 0xfff80080
	s_addc_u32 s35, s9, -1
	s_add_i32 s64, 0, 0x10000
	s_cmp_eq_u32 s63, 28
	s_cselect_b32 s37, s21, s35
	s_cselect_b32 s36, s23, s34
	s_cselect_b32 s35, s25, s62
	s_cselect_b32 s34, s27, s61
	s_add_i32 s66, 0, 0x14000
	v_lshl_add_u64 v[220:221], s[8:9], 0, v[190:191]
	s_add_i32 m0, s42, 0xc000
	s_nop 0
	global_load_lds_dwordx4 v[220:221], off
	v_lshl_add_u64 v[220:221], s[8:9], 0, v[188:189]
	s_add_i32 m0, s42, 0xe000
	s_nop 0
	global_load_lds_dwordx4 v[220:221], off
	v_add_u32_e32 v0, s64, v212
	ds_read_b128 v[66:69], v0
	ds_read_b128 v[70:73], v0 offset:1024
	ds_read_b128 v[74:77], v0 offset:2048
	ds_read_b128 v[78:81], v0 offset:3072
	v_add_u32_e32 v0, s66, v212
	ds_read_b128 v[130:133], v0
	ds_read_b128 v[142:145], v0 offset:1024
	ds_read_b128 v[146:149], v0 offset:2048
	ds_read_b128 v[158:161], v0 offset:3072
	ds_read_b128 v[162:165], v215
	ds_read_b128 v[166:169], v215 offset:1024
	ds_read_b128 v[170:173], v215 offset:2048
	ds_read_b128 v[192:195], v215 offset:3072
	ds_read_b128 v[196:199], v215 offset:4096
	ds_read_b128 v[200:203], v215 offset:5120
	ds_read_b128 v[204:207], v215 offset:6144
	ds_read_b128 v[208:211], v215 offset:7168
	s_waitcnt vmcnt(8)
	s_waitcnt lgkmcnt(0)
	s_barrier
	s_setprio 1
	v_mfma_f32_16x16x32_bf16 v[154:157], v[66:69], v[162:165], v[154:157]
	v_mfma_f32_16x16x32_bf16 v[150:153], v[74:77], v[162:165], v[150:153]
	v_mfma_f32_16x16x32_bf16 v[138:141], v[66:69], v[170:173], v[138:141]
	v_mfma_f32_16x16x32_bf16 v[134:137], v[74:77], v[170:173], v[134:137]
	v_mfma_f32_16x16x32_bf16 v[110:113], v[66:69], v[196:199], v[110:113]
	v_mfma_f32_16x16x32_bf16 v[106:109], v[74:77], v[196:199], v[106:109]
	v_mfma_f32_16x16x32_bf16 v[94:97], v[66:69], v[204:207], v[94:97]
	v_mfma_f32_16x16x32_bf16 v[90:93], v[74:77], v[204:207], v[90:93]
	v_mfma_f32_16x16x32_bf16 v[154:157], v[70:73], v[166:169], v[154:157]
	v_mfma_f32_16x16x32_bf16 v[150:153], v[78:81], v[166:169], v[150:153]
	v_mfma_f32_16x16x32_bf16 v[138:141], v[70:73], v[192:195], v[138:141]
	v_mfma_f32_16x16x32_bf16 v[134:137], v[78:81], v[192:195], v[134:137]
	v_mfma_f32_16x16x32_bf16 v[110:113], v[70:73], v[200:203], v[110:113]
	v_mfma_f32_16x16x32_bf16 v[106:109], v[78:81], v[200:203], v[106:109]
	v_mfma_f32_16x16x32_bf16 v[94:97], v[70:73], v[208:211], v[94:97]
	v_mfma_f32_16x16x32_bf16 v[90:93], v[78:81], v[208:211], v[90:93]
	v_mfma_f32_16x16x32_bf16 v[126:129], v[130:133], v[162:165], v[126:129]
	v_mfma_f32_16x16x32_bf16 v[114:117], v[146:149], v[162:165], v[114:117]
	v_mfma_f32_16x16x32_bf16 v[122:125], v[130:133], v[170:173], v[122:125]
	v_mfma_f32_16x16x32_bf16 v[118:121], v[146:149], v[170:173], v[118:121]
	v_mfma_f32_16x16x32_bf16 v[102:105], v[130:133], v[196:199], v[102:105]
	v_mfma_f32_16x16x32_bf16 v[98:101], v[146:149], v[196:199], v[98:101]
	v_mfma_f32_16x16x32_bf16 v[86:89], v[130:133], v[204:207], v[86:89]
	v_mfma_f32_16x16x32_bf16 v[82:85], v[146:149], v[204:207], v[82:85]
	v_mfma_f32_16x16x32_bf16 v[126:129], v[142:145], v[166:169], v[126:129]
	v_mfma_f32_16x16x32_bf16 v[114:117], v[158:161], v[166:169], v[114:117]
	v_mfma_f32_16x16x32_bf16 v[122:125], v[142:145], v[192:195], v[122:125]
	v_mfma_f32_16x16x32_bf16 v[118:121], v[158:161], v[192:195], v[118:121]
	v_mfma_f32_16x16x32_bf16 v[102:105], v[142:145], v[200:203], v[102:105]
	v_mfma_f32_16x16x32_bf16 v[98:101], v[158:161], v[200:203], v[98:101]
	v_mfma_f32_16x16x32_bf16 v[86:89], v[142:145], v[208:211], v[86:89]
	v_mfma_f32_16x16x32_bf16 v[82:85], v[158:161], v[208:211], v[82:85]
	s_setprio 0
	s_barrier
	s_add_i32 s64, s64, s41
	v_lshl_add_u64 v[220:221], s[34:35], 0, v[182:183]
	s_mov_b32 m0, s64
	s_nop 0
	global_load_lds_dwordx4 v[220:221], off
	s_add_i32 m0, s64, 0x2000
	s_add_u32 s64, s34, 0x80000
	v_lshl_add_u64 v[230:231], s[34:35], 0, v[178:179]
	s_addc_u32 s65, s35, 0
	s_add_i32 s66, s66, s41
	global_load_lds_dwordx4 v[230:231], off
	v_lshl_add_u64 v[232:233], s[64:65], 0, v[182:183]
	s_mov_b32 m0, s66
	v_lshl_add_u64 v[234:235], s[36:37], 0, v[180:181]
	global_load_lds_dwordx4 v[232:233], off
	v_lshl_add_u64 v[232:233], s[64:65], 0, v[178:179]
	s_add_i32 m0, s66, 0x2000
	s_nop 0
	global_load_lds_dwordx4 v[232:233], off
	v_lshl_add_u64 v[232:233], s[36:37], 0, v[184:185]
	s_mov_b32 m0, s42
	s_nop 0
	global_load_lds_dwordx4 v[232:233], off
	s_mov_b32 m0, s43
	s_nop 0
	global_load_lds_dwordx4 v[234:235], off
	ds_read_b128 v[162:165], v215 offset:16384
	ds_read_b128 v[166:169], v215 offset:17408
	ds_read_b128 v[170:173], v215 offset:18432
	ds_read_b128 v[192:195], v215 offset:19456
	ds_read_b128 v[196:199], v215 offset:20480
	ds_read_b128 v[200:203], v215 offset:21504
	ds_read_b128 v[204:207], v215 offset:22528
	ds_read_b128 v[208:211], v215 offset:23552
	s_waitcnt vmcnt(8)
	s_waitcnt lgkmcnt(0)
	s_barrier
	s_setprio 1
	v_mfma_f32_16x16x32_bf16 v[62:65], v[66:69], v[162:165], v[62:65]
	v_mfma_f32_16x16x32_bf16 v[58:61], v[74:77], v[162:165], v[58:61]
	v_mfma_f32_16x16x32_bf16 v[46:49], v[66:69], v[170:173], v[46:49]
	v_mfma_f32_16x16x32_bf16 v[42:45], v[74:77], v[170:173], v[42:45]
	v_mfma_f32_16x16x32_bf16 v[30:33], v[66:69], v[196:199], v[30:33]
	v_mfma_f32_16x16x32_bf16 v[26:29], v[74:77], v[196:199], v[26:29]
	v_mfma_f32_16x16x32_bf16 v[14:17], v[66:69], v[204:207], v[14:17]
	v_mfma_f32_16x16x32_bf16 v[10:13], v[74:77], v[204:207], v[10:13]
	v_mfma_f32_16x16x32_bf16 v[62:65], v[70:73], v[166:169], v[62:65]
	v_mfma_f32_16x16x32_bf16 v[58:61], v[78:81], v[166:169], v[58:61]
	v_mfma_f32_16x16x32_bf16 v[46:49], v[70:73], v[192:195], v[46:49]
	v_mfma_f32_16x16x32_bf16 v[42:45], v[78:81], v[192:195], v[42:45]
	v_mfma_f32_16x16x32_bf16 v[30:33], v[70:73], v[200:203], v[30:33]
	v_mfma_f32_16x16x32_bf16 v[26:29], v[78:81], v[200:203], v[26:29]
	v_mfma_f32_16x16x32_bf16 v[14:17], v[70:73], v[208:211], v[14:17]
	v_mfma_f32_16x16x32_bf16 v[10:13], v[78:81], v[208:211], v[10:13]
	v_mfma_f32_16x16x32_bf16 v[54:57], v[130:133], v[162:165], v[54:57]
	v_mfma_f32_16x16x32_bf16 v[50:53], v[146:149], v[162:165], v[50:53]
	v_mfma_f32_16x16x32_bf16 v[38:41], v[130:133], v[170:173], v[38:41]
	v_mfma_f32_16x16x32_bf16 v[34:37], v[146:149], v[170:173], v[34:37]
	v_mfma_f32_16x16x32_bf16 v[22:25], v[130:133], v[196:199], v[22:25]
	v_mfma_f32_16x16x32_bf16 v[18:21], v[146:149], v[196:199], v[18:21]
	v_mfma_f32_16x16x32_bf16 v[6:9], v[130:133], v[204:207], v[6:9]
	v_mfma_f32_16x16x32_bf16 v[2:5], v[146:149], v[204:207], v[2:5]
	v_mfma_f32_16x16x32_bf16 v[54:57], v[142:145], v[166:169], v[54:57]
	v_mfma_f32_16x16x32_bf16 v[50:53], v[158:161], v[166:169], v[50:53]
	v_mfma_f32_16x16x32_bf16 v[38:41], v[142:145], v[192:195], v[38:41]
	v_mfma_f32_16x16x32_bf16 v[34:37], v[158:161], v[192:195], v[34:37]
	v_mfma_f32_16x16x32_bf16 v[22:25], v[142:145], v[200:203], v[22:25]
	v_mfma_f32_16x16x32_bf16 v[18:21], v[158:161], v[200:203], v[18:21]
	v_mfma_f32_16x16x32_bf16 v[6:9], v[142:145], v[208:211], v[6:9]
	v_mfma_f32_16x16x32_bf16 v[2:5], v[158:161], v[208:211], v[2:5]
	s_setprio 0
	s_barrier
	s_add_i32 s64, 0, 0x18000
	s_add_i32 s65, 0, 0x1c000
	s_add_u32 s36, s36, 0x80000
	s_addc_u32 s37, s37, 0
	s_mov_b32 m0, s44
	v_lshl_add_u64 v[236:237], s[36:37], 0, v[184:185]
	global_load_lds_dwordx4 v[236:237], off
	v_lshl_add_u64 v[236:237], s[36:37], 0, v[180:181]
	s_mov_b32 m0, s45
	s_nop 0
	global_load_lds_dwordx4 v[236:237], off
	v_add_u32_e32 v0, s64, v212
	ds_read_b128 v[66:69], v0
	ds_read_b128 v[70:73], v0 offset:1024
	ds_read_b128 v[74:77], v0 offset:2048
	ds_read_b128 v[78:81], v0 offset:3072
	v_add_u32_e32 v0, s65, v212
	ds_read_b128 v[130:133], v0
	ds_read_b128 v[142:145], v0 offset:1024
	ds_read_b128 v[146:149], v0 offset:2048
	ds_read_b128 v[158:161], v0 offset:3072
	ds_read_b128 v[162:165], v215 offset:32768
	ds_read_b128 v[166:169], v215 offset:33792
	ds_read_b128 v[170:173], v215 offset:34816
	ds_read_b128 v[192:195], v215 offset:35840
	ds_read_b128 v[196:199], v215 offset:36864
	ds_read_b128 v[200:203], v215 offset:37888
	ds_read_b128 v[204:207], v215 offset:38912
	ds_read_b128 v[208:211], v215 offset:39936
	s_waitcnt vmcnt(8)
	s_waitcnt lgkmcnt(0)
	s_barrier
	s_setprio 1
	v_mfma_f32_16x16x32_bf16 v[154:157], v[66:69], v[162:165], v[154:157]
	v_mfma_f32_16x16x32_bf16 v[150:153], v[74:77], v[162:165], v[150:153]
	v_mfma_f32_16x16x32_bf16 v[138:141], v[66:69], v[170:173], v[138:141]
	v_mfma_f32_16x16x32_bf16 v[134:137], v[74:77], v[170:173], v[134:137]
	v_mfma_f32_16x16x32_bf16 v[110:113], v[66:69], v[196:199], v[110:113]
	v_mfma_f32_16x16x32_bf16 v[106:109], v[74:77], v[196:199], v[106:109]
	v_mfma_f32_16x16x32_bf16 v[94:97], v[66:69], v[204:207], v[94:97]
	v_mfma_f32_16x16x32_bf16 v[90:93], v[74:77], v[204:207], v[90:93]
	v_mfma_f32_16x16x32_bf16 v[154:157], v[70:73], v[166:169], v[154:157]
	v_mfma_f32_16x16x32_bf16 v[150:153], v[78:81], v[166:169], v[150:153]
	v_mfma_f32_16x16x32_bf16 v[138:141], v[70:73], v[192:195], v[138:141]
	v_mfma_f32_16x16x32_bf16 v[134:137], v[78:81], v[192:195], v[134:137]
	v_mfma_f32_16x16x32_bf16 v[110:113], v[70:73], v[200:203], v[110:113]
	v_mfma_f32_16x16x32_bf16 v[106:109], v[78:81], v[200:203], v[106:109]
	v_mfma_f32_16x16x32_bf16 v[94:97], v[70:73], v[208:211], v[94:97]
	v_mfma_f32_16x16x32_bf16 v[90:93], v[78:81], v[208:211], v[90:93]
	v_mfma_f32_16x16x32_bf16 v[126:129], v[130:133], v[162:165], v[126:129]
	v_mfma_f32_16x16x32_bf16 v[114:117], v[146:149], v[162:165], v[114:117]
	v_mfma_f32_16x16x32_bf16 v[122:125], v[130:133], v[170:173], v[122:125]
	v_mfma_f32_16x16x32_bf16 v[118:121], v[146:149], v[170:173], v[118:121]
	v_mfma_f32_16x16x32_bf16 v[102:105], v[130:133], v[196:199], v[102:105]
	v_mfma_f32_16x16x32_bf16 v[98:101], v[146:149], v[196:199], v[98:101]
	v_mfma_f32_16x16x32_bf16 v[86:89], v[130:133], v[204:207], v[86:89]
	v_mfma_f32_16x16x32_bf16 v[82:85], v[146:149], v[204:207], v[82:85]
	v_mfma_f32_16x16x32_bf16 v[126:129], v[142:145], v[166:169], v[126:129]
	v_mfma_f32_16x16x32_bf16 v[114:117], v[158:161], v[166:169], v[114:117]
	v_mfma_f32_16x16x32_bf16 v[122:125], v[142:145], v[192:195], v[122:125]
	v_mfma_f32_16x16x32_bf16 v[118:121], v[158:161], v[192:195], v[118:121]
	v_mfma_f32_16x16x32_bf16 v[102:105], v[142:145], v[200:203], v[102:105]
	v_mfma_f32_16x16x32_bf16 v[98:101], v[158:161], v[200:203], v[98:101]
	v_mfma_f32_16x16x32_bf16 v[86:89], v[142:145], v[208:211], v[86:89]
	v_mfma_f32_16x16x32_bf16 v[82:85], v[158:161], v[208:211], v[82:85]
	s_setprio 0
	s_barrier
	s_add_i32 s36, s64, s41
	v_lshl_add_u64 v[220:221], v[220:221], 0, s[96:97]
	s_mov_b32 m0, s36
	s_nop 0
	global_load_lds_dwordx4 v[220:221], off
	s_add_i32 m0, s36, 0x2000
	s_add_u32 s34, s34, 0x80080
	v_lshl_add_u64 v[220:221], v[230:231], 0, s[96:97]
	s_addc_u32 s35, s35, 0
	s_add_i32 s36, s65, s41
	global_load_lds_dwordx4 v[220:221], off
	v_lshl_add_u64 v[220:221], s[34:35], 0, v[182:183]
	s_mov_b32 m0, s36
	s_nop 0
	global_load_lds_dwordx4 v[220:221], off
	v_lshl_add_u64 v[220:221], s[34:35], 0, v[178:179]
	s_add_i32 m0, s36, 0x2000
	s_nop 0
	global_load_lds_dwordx4 v[220:221], off
	v_lshl_add_u64 v[220:221], v[232:233], 0, s[96:97]
	s_mov_b32 m0, s56
	s_nop 0
	global_load_lds_dwordx4 v[220:221], off
	v_lshl_add_u64 v[220:221], v[234:235], 0, s[96:97]
	s_mov_b32 m0, s57
	s_nop 0
	global_load_lds_dwordx4 v[220:221], off
	ds_read_b128 v[162:165], v215 offset:49152
	ds_read_b128 v[166:169], v215 offset:50176
	ds_read_b128 v[170:173], v215 offset:51200
	ds_read_b128 v[192:195], v215 offset:52224
	ds_read_b128 v[196:199], v215 offset:53248
	ds_read_b128 v[200:203], v215 offset:54272
	ds_read_b128 v[204:207], v215 offset:55296
	ds_read_b128 v[208:211], v215 offset:56320
	s_waitcnt vmcnt(8)
	s_waitcnt lgkmcnt(0)
	s_barrier
	s_setprio 1
	v_mfma_f32_16x16x32_bf16 v[62:65], v[66:69], v[162:165], v[62:65]
	v_mfma_f32_16x16x32_bf16 v[58:61], v[74:77], v[162:165], v[58:61]
	v_mfma_f32_16x16x32_bf16 v[46:49], v[66:69], v[170:173], v[46:49]
	v_mfma_f32_16x16x32_bf16 v[42:45], v[74:77], v[170:173], v[42:45]
	v_mfma_f32_16x16x32_bf16 v[30:33], v[66:69], v[196:199], v[30:33]
	v_mfma_f32_16x16x32_bf16 v[26:29], v[74:77], v[196:199], v[26:29]
	v_mfma_f32_16x16x32_bf16 v[14:17], v[66:69], v[204:207], v[14:17]
	v_mfma_f32_16x16x32_bf16 v[10:13], v[74:77], v[204:207], v[10:13]
	v_mfma_f32_16x16x32_bf16 v[62:65], v[70:73], v[166:169], v[62:65]
	v_mfma_f32_16x16x32_bf16 v[58:61], v[78:81], v[166:169], v[58:61]
	v_mfma_f32_16x16x32_bf16 v[46:49], v[70:73], v[192:195], v[46:49]
	v_mfma_f32_16x16x32_bf16 v[42:45], v[78:81], v[192:195], v[42:45]
	v_mfma_f32_16x16x32_bf16 v[30:33], v[70:73], v[200:203], v[30:33]
	v_mfma_f32_16x16x32_bf16 v[26:29], v[78:81], v[200:203], v[26:29]
	v_mfma_f32_16x16x32_bf16 v[14:17], v[70:73], v[208:211], v[14:17]
	v_mfma_f32_16x16x32_bf16 v[10:13], v[78:81], v[208:211], v[10:13]
	v_mfma_f32_16x16x32_bf16 v[54:57], v[130:133], v[162:165], v[54:57]
	v_mfma_f32_16x16x32_bf16 v[50:53], v[146:149], v[162:165], v[50:53]
	v_mfma_f32_16x16x32_bf16 v[38:41], v[130:133], v[170:173], v[38:41]
	v_mfma_f32_16x16x32_bf16 v[34:37], v[146:149], v[170:173], v[34:37]
	v_mfma_f32_16x16x32_bf16 v[22:25], v[130:133], v[196:199], v[22:25]
	v_mfma_f32_16x16x32_bf16 v[18:21], v[146:149], v[196:199], v[18:21]
	v_mfma_f32_16x16x32_bf16 v[6:9], v[130:133], v[204:207], v[6:9]
	v_mfma_f32_16x16x32_bf16 v[2:5], v[146:149], v[204:207], v[2:5]
	v_mfma_f32_16x16x32_bf16 v[54:57], v[142:145], v[166:169], v[54:57]
	v_mfma_f32_16x16x32_bf16 v[50:53], v[158:161], v[166:169], v[50:53]
	v_mfma_f32_16x16x32_bf16 v[38:41], v[142:145], v[192:195], v[38:41]
	v_mfma_f32_16x16x32_bf16 v[34:37], v[158:161], v[192:195], v[34:37]
	v_mfma_f32_16x16x32_bf16 v[22:25], v[142:145], v[200:203], v[22:25]
	v_mfma_f32_16x16x32_bf16 v[18:21], v[158:161], v[200:203], v[18:21]
	v_mfma_f32_16x16x32_bf16 v[6:9], v[142:145], v[208:211], v[6:9]
	v_mfma_f32_16x16x32_bf16 v[2:5], v[158:161], v[208:211], v[2:5]
	s_setprio 0
	s_barrier
	s_add_i32 s63, s63, 2
	s_add_u32 s61, s61, 0x100
	s_addc_u32 s62, s62, 0
	s_add_u32 s8, s8, 0x100
	s_addc_u32 s9, s9, 0
	s_cmp_gt_u32 s63, 29
	s_cbranch_scc0 .LBB0_617
	s_and_b64 vcc, exec, s[14:15]
	s_cbranch_vccz .LBB0_620
	s_barrier

.LBB0_744:
	s_add_u32 s44, s38, 0x100
	s_addc_u32 s45, s39, 0
	s_and_b64 s[46:47], s[46:47], exec
	s_cselect_b32 s51, s31, s45
	s_cselect_b32 s50, s88, s44
	s_cselect_b32 s47, s29, s43
	s_cselect_b32 s46, s90, s41
	s_add_i32 s93, 0, 0x10000
	s_add_i32 s94, 0, 0x14000
	v_add_u32_e32 v84, s93, v226
	v_add_u32_e32 v88, s94, v226
	ds_read_b128 v[72:75], v84
	ds_read_b128 v[76:79], v84 offset:1024
	ds_read_b128 v[80:83], v84 offset:2048
	ds_read_b128 v[84:87], v84 offset:3072
	ds_read_b128 v[154:157], v88
	ds_read_b128 v[158:161], v88 offset:1024
	ds_read_b128 v[182:185], v88 offset:2048
	ds_read_b128 v[186:189], v88 offset:3072
	v_lshl_add_u64 v[88:89], s[38:39], 0, v[180:181]
	s_add_i32 m0, s56, 0xc000
	s_nop 0
	global_load_lds_dwordx4 v[88:89], off
	v_lshl_add_u64 v[88:89], s[38:39], 0, v[178:179]
	s_add_i32 m0, s56, 0xe000
	s_nop 0
	global_load_lds_dwordx4 v[88:89], off
	ds_read_b128 v[190:193], v230
	ds_read_b128 v[194:197], v230 offset:1024
	ds_read_b128 v[198:201], v230 offset:2048
	ds_read_b128 v[202:205], v230 offset:3072
	ds_read_b128 v[206:209], v230 offset:4096
	ds_read_b128 v[210:213], v230 offset:5120
	ds_read_b128 v[214:217], v230 offset:6144
	ds_read_b128 v[236:239], v230 offset:7168
	s_waitcnt vmcnt(8)
	s_waitcnt lgkmcnt(0)
	s_barrier
	s_setprio 1
	v_mfma_f32_16x16x32_bf16 v[150:153], v[72:75], v[190:193], v[150:153]
	v_mfma_f32_16x16x32_bf16 v[146:149], v[80:83], v[190:193], v[146:149]
	v_mfma_f32_16x16x32_bf16 v[118:121], v[72:75], v[198:201], v[118:121]
	v_mfma_f32_16x16x32_bf16 v[114:117], v[80:83], v[198:201], v[114:117]
	v_mfma_f32_16x16x32_bf16 v[142:145], v[72:75], v[206:209], v[142:145]
	v_mfma_f32_16x16x32_bf16 v[134:137], v[80:83], v[206:209], v[134:137]
	v_mfma_f32_16x16x32_bf16 v[126:129], v[72:75], v[214:217], v[126:129]
	v_mfma_f32_16x16x32_bf16 v[122:125], v[80:83], v[214:217], v[122:125]
	v_mfma_f32_16x16x32_bf16 v[150:153], v[76:79], v[194:197], v[150:153]
	v_mfma_f32_16x16x32_bf16 v[146:149], v[84:87], v[194:197], v[146:149]
	v_mfma_f32_16x16x32_bf16 v[118:121], v[76:79], v[202:205], v[118:121]
	v_mfma_f32_16x16x32_bf16 v[114:117], v[84:87], v[202:205], v[114:117]
	v_mfma_f32_16x16x32_bf16 v[142:145], v[76:79], v[210:213], v[142:145]
	v_mfma_f32_16x16x32_bf16 v[134:137], v[84:87], v[210:213], v[134:137]
	v_mfma_f32_16x16x32_bf16 v[126:129], v[76:79], v[236:239], v[126:129]
	v_mfma_f32_16x16x32_bf16 v[122:125], v[84:87], v[236:239], v[122:125]
	v_mfma_f32_16x16x32_bf16 v[138:141], v[154:157], v[190:193], v[138:141]
	v_mfma_f32_16x16x32_bf16 v[130:133], v[182:185], v[190:193], v[130:133]
	v_mfma_f32_16x16x32_bf16 v[110:113], v[154:157], v[198:201], v[110:113]
	v_mfma_f32_16x16x32_bf16 v[106:109], v[182:185], v[198:201], v[106:109]
	v_mfma_f32_16x16x32_bf16 v[102:105], v[154:157], v[206:209], v[102:105]
	v_mfma_f32_16x16x32_bf16 v[98:101], v[182:185], v[206:209], v[98:101]
	v_mfma_f32_16x16x32_bf16 v[94:97], v[154:157], v[214:217], v[94:97]
	v_mfma_f32_16x16x32_bf16 v[88:91], v[182:185], v[214:217], v[90:93]
	v_mfma_f32_16x16x32_bf16 v[138:141], v[158:161], v[194:197], v[138:141]
	v_mfma_f32_16x16x32_bf16 v[130:133], v[186:189], v[194:197], v[130:133]
	v_mfma_f32_16x16x32_bf16 v[110:113], v[158:161], v[202:205], v[110:113]
	v_mfma_f32_16x16x32_bf16 v[106:109], v[186:189], v[202:205], v[106:109]
	v_mfma_f32_16x16x32_bf16 v[102:105], v[158:161], v[210:213], v[102:105]
	v_mfma_f32_16x16x32_bf16 v[98:101], v[186:189], v[210:213], v[98:101]
	v_mfma_f32_16x16x32_bf16 v[94:97], v[158:161], v[236:239], v[94:97]
	v_mfma_f32_16x16x32_bf16 v[88:91], v[186:189], v[236:239], v[88:91]
	s_setprio 0
	s_barrier
	s_add_i32 s38, s93, s55
	v_lshl_add_u64 v[220:221], s[46:47], 0, v[166:167]
	s_mov_b32 m0, s38
	s_nop 0
	global_load_lds_dwordx4 v[220:221], off
	s_add_i32 m0, s38, 0x2000
	s_add_u32 s38, s46, 0x80000
	v_lshl_add_u64 v[240:241], s[46:47], 0, v[162:163]
	s_addc_u32 s39, s47, 0
	s_add_i32 s93, s94, s55
	global_load_lds_dwordx4 v[240:241], off
	v_lshl_add_u64 v[92:93], s[38:39], 0, v[166:167]
	s_mov_b32 m0, s93
	v_lshl_add_u64 v[242:243], s[50:51], 0, v[168:169]
	global_load_lds_dwordx4 v[92:93], off
	v_lshl_add_u64 v[92:93], s[38:39], 0, v[162:163]
	s_add_i32 m0, s93, 0x2000
	v_lshl_add_u64 v[244:245], s[50:51], 0, v[164:165]
	global_load_lds_dwordx4 v[92:93], off
	s_mov_b32 m0, s56
	s_nop 0
	global_load_lds_dwordx4 v[242:243], off
	s_mov_b32 m0, s57
	s_nop 0
	global_load_lds_dwordx4 v[244:245], off
	ds_read_b128 v[190:193], v230 offset:16384
	ds_read_b128 v[194:197], v230 offset:17408
	ds_read_b128 v[198:201], v230 offset:18432
	ds_read_b128 v[202:205], v230 offset:19456
	ds_read_b128 v[206:209], v230 offset:20480
	ds_read_b128 v[210:213], v230 offset:21504
	ds_read_b128 v[214:217], v230 offset:22528
	ds_read_b128 v[236:239], v230 offset:23552
	s_waitcnt vmcnt(8)
	s_waitcnt lgkmcnt(0)
	s_barrier
	s_setprio 1
	v_mfma_f32_16x16x32_bf16 v[62:65], v[72:75], v[190:193], v[62:65]
	v_mfma_f32_16x16x32_bf16 v[58:61], v[80:83], v[190:193], v[58:61]
	v_mfma_f32_16x16x32_bf16 v[54:57], v[72:75], v[198:201], v[54:57]
	v_mfma_f32_16x16x32_bf16 v[46:49], v[80:83], v[198:201], v[46:49]
	v_mfma_f32_16x16x32_bf16 v[38:41], v[72:75], v[206:209], v[38:41]
	v_mfma_f32_16x16x32_bf16 v[30:33], v[80:83], v[206:209], v[30:33]
	v_mfma_f32_16x16x32_bf16 v[22:25], v[72:75], v[214:217], v[22:25]
	v_mfma_f32_16x16x32_bf16 v[14:17], v[80:83], v[214:217], v[14:17]
	v_mfma_f32_16x16x32_bf16 v[62:65], v[76:79], v[194:197], v[62:65]
	v_mfma_f32_16x16x32_bf16 v[58:61], v[84:87], v[194:197], v[58:61]
	v_mfma_f32_16x16x32_bf16 v[54:57], v[76:79], v[202:205], v[54:57]
	v_mfma_f32_16x16x32_bf16 v[46:49], v[84:87], v[202:205], v[46:49]
	v_mfma_f32_16x16x32_bf16 v[38:41], v[76:79], v[210:213], v[38:41]
	v_mfma_f32_16x16x32_bf16 v[30:33], v[84:87], v[210:213], v[30:33]
	v_mfma_f32_16x16x32_bf16 v[22:25], v[76:79], v[236:239], v[22:25]
	v_mfma_f32_16x16x32_bf16 v[14:17], v[84:87], v[236:239], v[14:17]
	v_mfma_f32_16x16x32_bf16 v[50:53], v[154:157], v[190:193], v[50:53]
	v_mfma_f32_16x16x32_bf16 v[42:45], v[182:185], v[190:193], v[42:45]
	v_mfma_f32_16x16x32_bf16 v[34:37], v[154:157], v[198:201], v[34:37]
	v_mfma_f32_16x16x32_bf16 v[26:29], v[182:185], v[198:201], v[26:29]
	v_mfma_f32_16x16x32_bf16 v[18:21], v[154:157], v[206:209], v[18:21]
	v_mfma_f32_16x16x32_bf16 v[10:13], v[182:185], v[206:209], v[10:13]
	v_mfma_f32_16x16x32_bf16 v[6:9], v[154:157], v[214:217], v[6:9]
	v_mfma_f32_16x16x32_bf16 v[2:5], v[182:185], v[214:217], v[2:5]
	v_mfma_f32_16x16x32_bf16 v[50:53], v[158:161], v[194:197], v[50:53]
	v_mfma_f32_16x16x32_bf16 v[42:45], v[186:189], v[194:197], v[42:45]
	v_mfma_f32_16x16x32_bf16 v[34:37], v[158:161], v[202:205], v[34:37]
	v_mfma_f32_16x16x32_bf16 v[26:29], v[186:189], v[202:205], v[26:29]
	v_mfma_f32_16x16x32_bf16 v[18:21], v[158:161], v[210:213], v[18:21]
	v_mfma_f32_16x16x32_bf16 v[10:13], v[186:189], v[210:213], v[10:13]
	v_mfma_f32_16x16x32_bf16 v[6:9], v[158:161], v[236:239], v[6:9]
	v_mfma_f32_16x16x32_bf16 v[2:5], v[186:189], v[236:239], v[2:5]
	s_setprio 0
	s_barrier
	s_add_i32 s93, 0, 0x18000
	s_add_i32 s94, 0, 0x1c000
	s_add_u32 s38, s50, 0x80000
	s_addc_u32 s39, s51, 0
	s_mov_b32 m0, s60
	v_add_u32_e32 v84, s93, v226
	v_add_u32_e32 v92, s94, v226
	ds_read_b128 v[72:75], v84
	ds_read_b128 v[76:79], v84 offset:1024
	ds_read_b128 v[80:83], v84 offset:2048
	ds_read_b128 v[84:87], v84 offset:3072
	ds_read_b128 v[154:157], v92
	ds_read_b128 v[158:161], v92 offset:1024
	ds_read_b128 v[182:185], v92 offset:2048
	ds_read_b128 v[186:189], v92 offset:3072
	v_lshl_add_u64 v[92:93], s[38:39], 0, v[168:169]
	global_load_lds_dwordx4 v[92:93], off
	v_lshl_add_u64 v[92:93], s[38:39], 0, v[164:165]
	s_mov_b32 m0, s61
	s_nop 0
	global_load_lds_dwordx4 v[92:93], off
	ds_read_b128 v[190:193], v230 offset:32768
	ds_read_b128 v[194:197], v230 offset:33792
	ds_read_b128 v[198:201], v230 offset:34816
	ds_read_b128 v[202:205], v230 offset:35840
	ds_read_b128 v[206:209], v230 offset:36864
	ds_read_b128 v[210:213], v230 offset:37888
	ds_read_b128 v[214:217], v230 offset:38912
	ds_read_b128 v[236:239], v230 offset:39936
	s_waitcnt vmcnt(8)
	s_waitcnt lgkmcnt(0)
	s_barrier
	s_setprio 1
	v_mfma_f32_16x16x32_bf16 v[150:153], v[72:75], v[190:193], v[150:153]
	v_mfma_f32_16x16x32_bf16 v[146:149], v[80:83], v[190:193], v[146:149]
	v_mfma_f32_16x16x32_bf16 v[118:121], v[72:75], v[198:201], v[118:121]
	v_mfma_f32_16x16x32_bf16 v[114:117], v[80:83], v[198:201], v[114:117]
	v_mfma_f32_16x16x32_bf16 v[142:145], v[72:75], v[206:209], v[142:145]
	v_mfma_f32_16x16x32_bf16 v[134:137], v[80:83], v[206:209], v[134:137]
	v_mfma_f32_16x16x32_bf16 v[126:129], v[72:75], v[214:217], v[126:129]
	v_mfma_f32_16x16x32_bf16 v[122:125], v[80:83], v[214:217], v[122:125]
	v_mfma_f32_16x16x32_bf16 v[150:153], v[76:79], v[194:197], v[150:153]
	v_mfma_f32_16x16x32_bf16 v[146:149], v[84:87], v[194:197], v[146:149]
	v_mfma_f32_16x16x32_bf16 v[118:121], v[76:79], v[202:205], v[118:121]
	v_mfma_f32_16x16x32_bf16 v[114:117], v[84:87], v[202:205], v[114:117]
	v_mfma_f32_16x16x32_bf16 v[142:145], v[76:79], v[210:213], v[142:145]
	v_mfma_f32_16x16x32_bf16 v[134:137], v[84:87], v[210:213], v[134:137]
	v_mfma_f32_16x16x32_bf16 v[126:129], v[76:79], v[236:239], v[126:129]
	v_mfma_f32_16x16x32_bf16 v[122:125], v[84:87], v[236:239], v[122:125]
	v_mfma_f32_16x16x32_bf16 v[138:141], v[154:157], v[190:193], v[138:141]
	v_mfma_f32_16x16x32_bf16 v[130:133], v[182:185], v[190:193], v[130:133]
	v_mfma_f32_16x16x32_bf16 v[110:113], v[154:157], v[198:201], v[110:113]
	v_mfma_f32_16x16x32_bf16 v[106:109], v[182:185], v[198:201], v[106:109]
	v_mfma_f32_16x16x32_bf16 v[102:105], v[154:157], v[206:209], v[102:105]
	v_mfma_f32_16x16x32_bf16 v[98:101], v[182:185], v[206:209], v[98:101]
	v_mfma_f32_16x16x32_bf16 v[92:95], v[154:157], v[214:217], v[94:97]
	v_mfma_f32_16x16x32_bf16 v[88:91], v[182:185], v[214:217], v[88:91]
	v_mfma_f32_16x16x32_bf16 v[138:141], v[158:161], v[194:197], v[138:141]
	v_mfma_f32_16x16x32_bf16 v[130:133], v[186:189], v[194:197], v[130:133]
	v_mfma_f32_16x16x32_bf16 v[110:113], v[158:161], v[202:205], v[110:113]
	v_mfma_f32_16x16x32_bf16 v[106:109], v[186:189], v[202:205], v[106:109]
	v_mfma_f32_16x16x32_bf16 v[102:105], v[158:161], v[210:213], v[102:105]
	v_mfma_f32_16x16x32_bf16 v[98:101], v[186:189], v[210:213], v[98:101]
	v_mfma_f32_16x16x32_bf16 v[94:97], v[158:161], v[236:239], v[92:95]
	v_mfma_f32_16x16x32_bf16 v[90:93], v[186:189], v[236:239], v[88:91]
	s_setprio 0
	s_barrier
	s_add_i32 s38, s93, s55
	v_lshl_add_u64 v[88:89], v[220:221], 0, s[96:97]
	s_mov_b32 m0, s38
	s_nop 0
	global_load_lds_dwordx4 v[88:89], off
	s_add_i32 m0, s38, 0x2000
	s_add_u32 s38, s46, 0x80080
	v_lshl_add_u64 v[88:89], v[240:241], 0, s[96:97]
	s_addc_u32 s39, s47, 0
	s_add_i32 s46, s94, s55
	global_load_lds_dwordx4 v[88:89], off
	v_lshl_add_u64 v[88:89], s[38:39], 0, v[166:167]
	s_mov_b32 m0, s46
	s_nop 0
	global_load_lds_dwordx4 v[88:89], off
	v_lshl_add_u64 v[88:89], s[38:39], 0, v[162:163]
	s_add_i32 m0, s46, 0x2000
	s_nop 0
	global_load_lds_dwordx4 v[88:89], off
	v_lshl_add_u64 v[88:89], v[242:243], 0, s[96:97]
	s_mov_b32 m0, s75
	s_nop 0
	global_load_lds_dwordx4 v[88:89], off
	v_lshl_add_u64 v[88:89], v[244:245], 0, s[96:97]
	s_mov_b32 m0, s76
	s_nop 0
	global_load_lds_dwordx4 v[88:89], off
	ds_read_b128 v[190:193], v230 offset:49152
	ds_read_b128 v[194:197], v230 offset:50176
	ds_read_b128 v[198:201], v230 offset:51200
	ds_read_b128 v[202:205], v230 offset:52224
	ds_read_b128 v[206:209], v230 offset:53248
	ds_read_b128 v[210:213], v230 offset:54272
	ds_read_b128 v[214:217], v230 offset:55296
	ds_read_b128 v[236:239], v230 offset:56320
	s_waitcnt vmcnt(8)
	s_waitcnt lgkmcnt(0)
	s_barrier
	s_setprio 1
	v_mfma_f32_16x16x32_bf16 v[62:65], v[72:75], v[190:193], v[62:65]
	v_mfma_f32_16x16x32_bf16 v[58:61], v[80:83], v[190:193], v[58:61]
	v_mfma_f32_16x16x32_bf16 v[54:57], v[72:75], v[198:201], v[54:57]
	v_mfma_f32_16x16x32_bf16 v[46:49], v[80:83], v[198:201], v[46:49]
	v_mfma_f32_16x16x32_bf16 v[38:41], v[72:75], v[206:209], v[38:41]
	v_mfma_f32_16x16x32_bf16 v[30:33], v[80:83], v[206:209], v[30:33]
	v_mfma_f32_16x16x32_bf16 v[22:25], v[72:75], v[214:217], v[22:25]
	v_mfma_f32_16x16x32_bf16 v[14:17], v[80:83], v[214:217], v[14:17]
	v_mfma_f32_16x16x32_bf16 v[62:65], v[76:79], v[194:197], v[62:65]
	v_mfma_f32_16x16x32_bf16 v[58:61], v[84:87], v[194:197], v[58:61]
	v_mfma_f32_16x16x32_bf16 v[54:57], v[76:79], v[202:205], v[54:57]
	v_mfma_f32_16x16x32_bf16 v[46:49], v[84:87], v[202:205], v[46:49]
	v_mfma_f32_16x16x32_bf16 v[38:41], v[76:79], v[210:213], v[38:41]
	v_mfma_f32_16x16x32_bf16 v[30:33], v[84:87], v[210:213], v[30:33]
	v_mfma_f32_16x16x32_bf16 v[22:25], v[76:79], v[236:239], v[22:25]
	v_mfma_f32_16x16x32_bf16 v[14:17], v[84:87], v[236:239], v[14:17]
	v_mfma_f32_16x16x32_bf16 v[50:53], v[154:157], v[190:193], v[50:53]
	v_mfma_f32_16x16x32_bf16 v[42:45], v[182:185], v[190:193], v[42:45]
	v_mfma_f32_16x16x32_bf16 v[34:37], v[154:157], v[198:201], v[34:37]
	v_mfma_f32_16x16x32_bf16 v[26:29], v[182:185], v[198:201], v[26:29]
	v_mfma_f32_16x16x32_bf16 v[18:21], v[154:157], v[206:209], v[18:21]
	v_mfma_f32_16x16x32_bf16 v[10:13], v[182:185], v[206:209], v[10:13]
	v_mfma_f32_16x16x32_bf16 v[6:9], v[154:157], v[214:217], v[6:9]
	v_mfma_f32_16x16x32_bf16 v[2:5], v[182:185], v[214:217], v[2:5]
	v_mfma_f32_16x16x32_bf16 v[50:53], v[158:161], v[194:197], v[50:53]
	v_mfma_f32_16x16x32_bf16 v[42:45], v[186:189], v[194:197], v[42:45]
	v_mfma_f32_16x16x32_bf16 v[34:37], v[158:161], v[202:205], v[34:37]
	v_mfma_f32_16x16x32_bf16 v[26:29], v[186:189], v[202:205], v[26:29]
	v_mfma_f32_16x16x32_bf16 v[18:21], v[158:161], v[210:213], v[18:21]
	v_mfma_f32_16x16x32_bf16 v[10:13], v[186:189], v[210:213], v[10:13]
	v_mfma_f32_16x16x32_bf16 v[6:9], v[158:161], v[236:239], v[6:9]
	v_mfma_f32_16x16x32_bf16 v[2:5], v[186:189], v[236:239], v[2:5]
	s_setprio 0
	s_barrier
	s_add_i32 s91, s91, 2
	s_add_u32 s41, s41, 0x100
	s_addc_u32 s43, s43, 0
	s_cmp_gt_u32 s91, 29
	s_mov_b64 s[38:39], s[44:45]
	s_cbranch_scc1 .LBB0_755

.LBB0_905:
	s_add_u32 s8, s26, 0x100
	s_addc_u32 s9, s27, 0
	s_add_i32 s61, 0, 0x10000
	s_cmpk_eq_i32 s60, 0x54
	s_cselect_b32 s31, s23, s9
	s_cselect_b32 s30, s22, s8
	s_cselect_b32 s29, s25, s21
	s_cselect_b32 s28, s24, s19
	s_add_i32 s62, 0, 0x14000
	v_lshl_add_u64 v[220:221], s[26:27], 0, v[190:191]
	s_add_i32 m0, s39, 0xc000
	s_nop 0
	global_load_lds_dwordx4 v[220:221], off
	v_lshl_add_u64 v[220:221], s[26:27], 0, v[188:189]
	s_add_i32 m0, s39, 0xe000
	s_nop 0
	global_load_lds_dwordx4 v[220:221], off
	v_add_u32_e32 v0, s61, v212
	ds_read_b128 v[66:69], v0
	ds_read_b128 v[70:73], v0 offset:1024
	ds_read_b128 v[74:77], v0 offset:2048
	ds_read_b128 v[78:81], v0 offset:3072
	v_add_u32_e32 v0, s62, v212
	ds_read_b128 v[130:133], v0
	ds_read_b128 v[142:145], v0 offset:1024
	ds_read_b128 v[146:149], v0 offset:2048
	ds_read_b128 v[158:161], v0 offset:3072
	ds_read_b128 v[162:165], v215
	ds_read_b128 v[166:169], v215 offset:1024
	ds_read_b128 v[170:173], v215 offset:2048
	ds_read_b128 v[192:195], v215 offset:3072
	ds_read_b128 v[196:199], v215 offset:4096
	ds_read_b128 v[200:203], v215 offset:5120
	ds_read_b128 v[204:207], v215 offset:6144
	ds_read_b128 v[208:211], v215 offset:7168
	s_waitcnt vmcnt(8)
	s_waitcnt lgkmcnt(0)
	s_barrier
	s_setprio 1
	v_mfma_f32_16x16x32_bf16 v[154:157], v[66:69], v[162:165], v[154:157]
	v_mfma_f32_16x16x32_bf16 v[150:153], v[74:77], v[162:165], v[150:153]
	v_mfma_f32_16x16x32_bf16 v[138:141], v[66:69], v[170:173], v[138:141]
	v_mfma_f32_16x16x32_bf16 v[134:137], v[74:77], v[170:173], v[134:137]
	v_mfma_f32_16x16x32_bf16 v[110:113], v[66:69], v[196:199], v[110:113]
	v_mfma_f32_16x16x32_bf16 v[106:109], v[74:77], v[196:199], v[106:109]
	v_mfma_f32_16x16x32_bf16 v[94:97], v[66:69], v[204:207], v[94:97]
	v_mfma_f32_16x16x32_bf16 v[90:93], v[74:77], v[204:207], v[90:93]
	v_mfma_f32_16x16x32_bf16 v[154:157], v[70:73], v[166:169], v[154:157]
	v_mfma_f32_16x16x32_bf16 v[150:153], v[78:81], v[166:169], v[150:153]
	v_mfma_f32_16x16x32_bf16 v[138:141], v[70:73], v[192:195], v[138:141]
	v_mfma_f32_16x16x32_bf16 v[134:137], v[78:81], v[192:195], v[134:137]
	v_mfma_f32_16x16x32_bf16 v[110:113], v[70:73], v[200:203], v[110:113]
	v_mfma_f32_16x16x32_bf16 v[106:109], v[78:81], v[200:203], v[106:109]
	v_mfma_f32_16x16x32_bf16 v[94:97], v[70:73], v[208:211], v[94:97]
	v_mfma_f32_16x16x32_bf16 v[90:93], v[78:81], v[208:211], v[90:93]
	v_mfma_f32_16x16x32_bf16 v[126:129], v[130:133], v[162:165], v[126:129]
	v_mfma_f32_16x16x32_bf16 v[114:117], v[146:149], v[162:165], v[114:117]
	v_mfma_f32_16x16x32_bf16 v[122:125], v[130:133], v[170:173], v[122:125]
	v_mfma_f32_16x16x32_bf16 v[118:121], v[146:149], v[170:173], v[118:121]
	v_mfma_f32_16x16x32_bf16 v[102:105], v[130:133], v[196:199], v[102:105]
	v_mfma_f32_16x16x32_bf16 v[98:101], v[146:149], v[196:199], v[98:101]
	v_mfma_f32_16x16x32_bf16 v[86:89], v[130:133], v[204:207], v[86:89]
	v_mfma_f32_16x16x32_bf16 v[82:85], v[146:149], v[204:207], v[82:85]
	v_mfma_f32_16x16x32_bf16 v[126:129], v[142:145], v[166:169], v[126:129]
	v_mfma_f32_16x16x32_bf16 v[114:117], v[158:161], v[166:169], v[114:117]
	v_mfma_f32_16x16x32_bf16 v[122:125], v[142:145], v[192:195], v[122:125]
	v_mfma_f32_16x16x32_bf16 v[118:121], v[158:161], v[192:195], v[118:121]
	v_mfma_f32_16x16x32_bf16 v[102:105], v[142:145], v[200:203], v[102:105]
	v_mfma_f32_16x16x32_bf16 v[98:101], v[158:161], v[200:203], v[98:101]
	v_mfma_f32_16x16x32_bf16 v[86:89], v[142:145], v[208:211], v[86:89]
	v_mfma_f32_16x16x32_bf16 v[82:85], v[158:161], v[208:211], v[82:85]
	s_setprio 0
	s_barrier
	s_add_i32 s26, s61, s38
	v_lshl_add_u64 v[220:221], s[28:29], 0, v[182:183]
	s_mov_b32 m0, s26
	s_nop 0
	global_load_lds_dwordx4 v[220:221], off
	s_add_i32 m0, s26, 0x2000
	s_add_u32 s26, s28, 0x160000
	v_lshl_add_u64 v[230:231], s[28:29], 0, v[178:179]
	s_addc_u32 s27, s29, 0
	s_add_i32 s61, s62, s38
	global_load_lds_dwordx4 v[230:231], off
	v_lshl_add_u64 v[232:233], s[26:27], 0, v[182:183]
	s_mov_b32 m0, s61
	v_lshl_add_u64 v[234:235], s[30:31], 0, v[180:181]
	global_load_lds_dwordx4 v[232:233], off
	v_lshl_add_u64 v[232:233], s[26:27], 0, v[178:179]
	s_add_i32 m0, s61, 0x2000
	s_nop 0
	global_load_lds_dwordx4 v[232:233], off
	v_lshl_add_u64 v[232:233], s[30:31], 0, v[184:185]
	s_mov_b32 m0, s39
	s_nop 0
	global_load_lds_dwordx4 v[232:233], off
	s_mov_b32 m0, s40
	s_nop 0
	global_load_lds_dwordx4 v[234:235], off
	ds_read_b128 v[162:165], v215 offset:16384
	ds_read_b128 v[166:169], v215 offset:17408
	ds_read_b128 v[170:173], v215 offset:18432
	ds_read_b128 v[192:195], v215 offset:19456
	ds_read_b128 v[196:199], v215 offset:20480
	ds_read_b128 v[200:203], v215 offset:21504
	ds_read_b128 v[204:207], v215 offset:22528
	ds_read_b128 v[208:211], v215 offset:23552
	s_waitcnt vmcnt(8)
	s_waitcnt lgkmcnt(0)
	s_barrier
	s_setprio 1
	v_mfma_f32_16x16x32_bf16 v[62:65], v[66:69], v[162:165], v[62:65]
	v_mfma_f32_16x16x32_bf16 v[58:61], v[74:77], v[162:165], v[58:61]
	v_mfma_f32_16x16x32_bf16 v[46:49], v[66:69], v[170:173], v[46:49]
	v_mfma_f32_16x16x32_bf16 v[42:45], v[74:77], v[170:173], v[42:45]
	v_mfma_f32_16x16x32_bf16 v[30:33], v[66:69], v[196:199], v[30:33]
	v_mfma_f32_16x16x32_bf16 v[26:29], v[74:77], v[196:199], v[26:29]
	v_mfma_f32_16x16x32_bf16 v[14:17], v[66:69], v[204:207], v[14:17]
	v_mfma_f32_16x16x32_bf16 v[10:13], v[74:77], v[204:207], v[10:13]
	v_mfma_f32_16x16x32_bf16 v[62:65], v[70:73], v[166:169], v[62:65]
	v_mfma_f32_16x16x32_bf16 v[58:61], v[78:81], v[166:169], v[58:61]
	v_mfma_f32_16x16x32_bf16 v[46:49], v[70:73], v[192:195], v[46:49]
	v_mfma_f32_16x16x32_bf16 v[42:45], v[78:81], v[192:195], v[42:45]
	v_mfma_f32_16x16x32_bf16 v[30:33], v[70:73], v[200:203], v[30:33]
	v_mfma_f32_16x16x32_bf16 v[26:29], v[78:81], v[200:203], v[26:29]
	v_mfma_f32_16x16x32_bf16 v[14:17], v[70:73], v[208:211], v[14:17]
	v_mfma_f32_16x16x32_bf16 v[10:13], v[78:81], v[208:211], v[10:13]
	v_mfma_f32_16x16x32_bf16 v[54:57], v[130:133], v[162:165], v[54:57]
	v_mfma_f32_16x16x32_bf16 v[50:53], v[146:149], v[162:165], v[50:53]
	v_mfma_f32_16x16x32_bf16 v[38:41], v[130:133], v[170:173], v[38:41]
	v_mfma_f32_16x16x32_bf16 v[34:37], v[146:149], v[170:173], v[34:37]
	v_mfma_f32_16x16x32_bf16 v[22:25], v[130:133], v[196:199], v[22:25]
	v_mfma_f32_16x16x32_bf16 v[18:21], v[146:149], v[196:199], v[18:21]
	v_mfma_f32_16x16x32_bf16 v[6:9], v[130:133], v[204:207], v[6:9]
	v_mfma_f32_16x16x32_bf16 v[2:5], v[146:149], v[204:207], v[2:5]
	v_mfma_f32_16x16x32_bf16 v[54:57], v[142:145], v[166:169], v[54:57]
	v_mfma_f32_16x16x32_bf16 v[50:53], v[158:161], v[166:169], v[50:53]
	v_mfma_f32_16x16x32_bf16 v[38:41], v[142:145], v[192:195], v[38:41]
	v_mfma_f32_16x16x32_bf16 v[34:37], v[158:161], v[192:195], v[34:37]
	v_mfma_f32_16x16x32_bf16 v[22:25], v[142:145], v[200:203], v[22:25]
	v_mfma_f32_16x16x32_bf16 v[18:21], v[158:161], v[200:203], v[18:21]
	v_mfma_f32_16x16x32_bf16 v[6:9], v[142:145], v[208:211], v[6:9]
	v_mfma_f32_16x16x32_bf16 v[2:5], v[158:161], v[208:211], v[2:5]
	s_setprio 0
	s_barrier
	s_add_i32 s61, 0, 0x18000
	s_add_i32 s62, 0, 0x1c000
	s_add_u32 s26, s30, 0x160000
	s_addc_u32 s27, s31, 0
	s_mov_b32 m0, s41
	v_lshl_add_u64 v[236:237], s[26:27], 0, v[184:185]
	global_load_lds_dwordx4 v[236:237], off
	v_lshl_add_u64 v[236:237], s[26:27], 0, v[180:181]
	s_mov_b32 m0, s42
	s_nop 0
	global_load_lds_dwordx4 v[236:237], off
	v_add_u32_e32 v0, s61, v212
	ds_read_b128 v[66:69], v0
	ds_read_b128 v[70:73], v0 offset:1024
	ds_read_b128 v[74:77], v0 offset:2048
	ds_read_b128 v[78:81], v0 offset:3072
	v_add_u32_e32 v0, s62, v212
	ds_read_b128 v[130:133], v0
	ds_read_b128 v[142:145], v0 offset:1024
	ds_read_b128 v[146:149], v0 offset:2048
	ds_read_b128 v[158:161], v0 offset:3072
	ds_read_b128 v[162:165], v215 offset:32768
	ds_read_b128 v[166:169], v215 offset:33792
	ds_read_b128 v[170:173], v215 offset:34816
	ds_read_b128 v[192:195], v215 offset:35840
	ds_read_b128 v[196:199], v215 offset:36864
	ds_read_b128 v[200:203], v215 offset:37888
	ds_read_b128 v[204:207], v215 offset:38912
	ds_read_b128 v[208:211], v215 offset:39936
	s_waitcnt vmcnt(8)
	s_waitcnt lgkmcnt(0)
	s_barrier
	s_setprio 1
	v_mfma_f32_16x16x32_bf16 v[154:157], v[66:69], v[162:165], v[154:157]
	v_mfma_f32_16x16x32_bf16 v[150:153], v[74:77], v[162:165], v[150:153]
	v_mfma_f32_16x16x32_bf16 v[138:141], v[66:69], v[170:173], v[138:141]
	v_mfma_f32_16x16x32_bf16 v[134:137], v[74:77], v[170:173], v[134:137]
	v_mfma_f32_16x16x32_bf16 v[110:113], v[66:69], v[196:199], v[110:113]
	v_mfma_f32_16x16x32_bf16 v[106:109], v[74:77], v[196:199], v[106:109]
	v_mfma_f32_16x16x32_bf16 v[94:97], v[66:69], v[204:207], v[94:97]
	v_mfma_f32_16x16x32_bf16 v[90:93], v[74:77], v[204:207], v[90:93]
	v_mfma_f32_16x16x32_bf16 v[154:157], v[70:73], v[166:169], v[154:157]
	v_mfma_f32_16x16x32_bf16 v[150:153], v[78:81], v[166:169], v[150:153]
	v_mfma_f32_16x16x32_bf16 v[138:141], v[70:73], v[192:195], v[138:141]
	v_mfma_f32_16x16x32_bf16 v[134:137], v[78:81], v[192:195], v[134:137]
	v_mfma_f32_16x16x32_bf16 v[110:113], v[70:73], v[200:203], v[110:113]
	v_mfma_f32_16x16x32_bf16 v[106:109], v[78:81], v[200:203], v[106:109]
	v_mfma_f32_16x16x32_bf16 v[94:97], v[70:73], v[208:211], v[94:97]
	v_mfma_f32_16x16x32_bf16 v[90:93], v[78:81], v[208:211], v[90:93]
	v_mfma_f32_16x16x32_bf16 v[126:129], v[130:133], v[162:165], v[126:129]
	v_mfma_f32_16x16x32_bf16 v[114:117], v[146:149], v[162:165], v[114:117]
	v_mfma_f32_16x16x32_bf16 v[122:125], v[130:133], v[170:173], v[122:125]
	v_mfma_f32_16x16x32_bf16 v[118:121], v[146:149], v[170:173], v[118:121]
	v_mfma_f32_16x16x32_bf16 v[102:105], v[130:133], v[196:199], v[102:105]
	v_mfma_f32_16x16x32_bf16 v[98:101], v[146:149], v[196:199], v[98:101]
	v_mfma_f32_16x16x32_bf16 v[86:89], v[130:133], v[204:207], v[86:89]
	v_mfma_f32_16x16x32_bf16 v[82:85], v[146:149], v[204:207], v[82:85]
	v_mfma_f32_16x16x32_bf16 v[126:129], v[142:145], v[166:169], v[126:129]
	v_mfma_f32_16x16x32_bf16 v[114:117], v[158:161], v[166:169], v[114:117]
	v_mfma_f32_16x16x32_bf16 v[122:125], v[142:145], v[192:195], v[122:125]
	v_mfma_f32_16x16x32_bf16 v[118:121], v[158:161], v[192:195], v[118:121]
	v_mfma_f32_16x16x32_bf16 v[102:105], v[142:145], v[200:203], v[102:105]
	v_mfma_f32_16x16x32_bf16 v[98:101], v[158:161], v[200:203], v[98:101]
	v_mfma_f32_16x16x32_bf16 v[86:89], v[142:145], v[208:211], v[86:89]
	v_mfma_f32_16x16x32_bf16 v[82:85], v[158:161], v[208:211], v[82:85]
	s_setprio 0
	s_barrier
	s_add_i32 s26, s61, s38
	v_lshl_add_u64 v[220:221], v[220:221], 0, s[96:97]
	s_mov_b32 m0, s26
	s_nop 0
	global_load_lds_dwordx4 v[220:221], off
	s_add_i32 m0, s26, 0x2000
	s_add_u32 s26, s28, 0x160080
	v_lshl_add_u64 v[220:221], v[230:231], 0, s[96:97]
	s_addc_u32 s27, s29, 0
	s_add_i32 s28, s62, s38
	global_load_lds_dwordx4 v[220:221], off
	v_lshl_add_u64 v[220:221], s[26:27], 0, v[182:183]
	s_mov_b32 m0, s28
	s_nop 0
	global_load_lds_dwordx4 v[220:221], off
	v_lshl_add_u64 v[220:221], s[26:27], 0, v[178:179]
	s_add_i32 m0, s28, 0x2000
	s_nop 0
	global_load_lds_dwordx4 v[220:221], off
	v_lshl_add_u64 v[220:221], v[232:233], 0, s[96:97]
	s_mov_b32 m0, s54
	s_nop 0
	global_load_lds_dwordx4 v[220:221], off
	v_lshl_add_u64 v[220:221], v[234:235], 0, s[96:97]
	s_mov_b32 m0, s55
	s_nop 0
	global_load_lds_dwordx4 v[220:221], off
	ds_read_b128 v[162:165], v215 offset:49152
	ds_read_b128 v[166:169], v215 offset:50176
	ds_read_b128 v[170:173], v215 offset:51200
	ds_read_b128 v[192:195], v215 offset:52224
	ds_read_b128 v[196:199], v215 offset:53248
	ds_read_b128 v[200:203], v215 offset:54272
	ds_read_b128 v[204:207], v215 offset:55296
	ds_read_b128 v[208:211], v215 offset:56320
	s_waitcnt vmcnt(8)
	s_waitcnt lgkmcnt(0)
	s_barrier
	s_setprio 1
	v_mfma_f32_16x16x32_bf16 v[62:65], v[66:69], v[162:165], v[62:65]
	v_mfma_f32_16x16x32_bf16 v[58:61], v[74:77], v[162:165], v[58:61]
	v_mfma_f32_16x16x32_bf16 v[46:49], v[66:69], v[170:173], v[46:49]
	v_mfma_f32_16x16x32_bf16 v[42:45], v[74:77], v[170:173], v[42:45]
	v_mfma_f32_16x16x32_bf16 v[30:33], v[66:69], v[196:199], v[30:33]
	v_mfma_f32_16x16x32_bf16 v[26:29], v[74:77], v[196:199], v[26:29]
	v_mfma_f32_16x16x32_bf16 v[14:17], v[66:69], v[204:207], v[14:17]
	v_mfma_f32_16x16x32_bf16 v[10:13], v[74:77], v[204:207], v[10:13]
	v_mfma_f32_16x16x32_bf16 v[62:65], v[70:73], v[166:169], v[62:65]
	v_mfma_f32_16x16x32_bf16 v[58:61], v[78:81], v[166:169], v[58:61]
	v_mfma_f32_16x16x32_bf16 v[46:49], v[70:73], v[192:195], v[46:49]
	v_mfma_f32_16x16x32_bf16 v[42:45], v[78:81], v[192:195], v[42:45]
	v_mfma_f32_16x16x32_bf16 v[30:33], v[70:73], v[200:203], v[30:33]
	v_mfma_f32_16x16x32_bf16 v[26:29], v[78:81], v[200:203], v[26:29]
	v_mfma_f32_16x16x32_bf16 v[14:17], v[70:73], v[208:211], v[14:17]
	v_mfma_f32_16x16x32_bf16 v[10:13], v[78:81], v[208:211], v[10:13]
	v_mfma_f32_16x16x32_bf16 v[54:57], v[130:133], v[162:165], v[54:57]
	v_mfma_f32_16x16x32_bf16 v[50:53], v[146:149], v[162:165], v[50:53]
	v_mfma_f32_16x16x32_bf16 v[38:41], v[130:133], v[170:173], v[38:41]
	v_mfma_f32_16x16x32_bf16 v[34:37], v[146:149], v[170:173], v[34:37]
	v_mfma_f32_16x16x32_bf16 v[22:25], v[130:133], v[196:199], v[22:25]
	v_mfma_f32_16x16x32_bf16 v[18:21], v[146:149], v[196:199], v[18:21]
	v_mfma_f32_16x16x32_bf16 v[6:9], v[130:133], v[204:207], v[6:9]
	v_mfma_f32_16x16x32_bf16 v[2:5], v[146:149], v[204:207], v[2:5]
	v_mfma_f32_16x16x32_bf16 v[54:57], v[142:145], v[166:169], v[54:57]
	v_mfma_f32_16x16x32_bf16 v[50:53], v[158:161], v[166:169], v[50:53]
	v_mfma_f32_16x16x32_bf16 v[38:41], v[142:145], v[192:195], v[38:41]
	v_mfma_f32_16x16x32_bf16 v[34:37], v[158:161], v[192:195], v[34:37]
	v_mfma_f32_16x16x32_bf16 v[22:25], v[142:145], v[200:203], v[22:25]
	v_mfma_f32_16x16x32_bf16 v[18:21], v[158:161], v[200:203], v[18:21]
	v_mfma_f32_16x16x32_bf16 v[6:9], v[142:145], v[208:211], v[6:9]
	v_mfma_f32_16x16x32_bf16 v[2:5], v[158:161], v[208:211], v[2:5]
	s_setprio 0
	s_barrier
	s_add_i32 s60, s60, 2
	s_add_u32 s19, s19, 0x100
	s_addc_u32 s21, s21, 0
	s_cmpk_gt_u32 s60, 0x55
	s_mov_b64 s[26:27], s[8:9]
	s_cbranch_scc0 .LBB0_905
	s_and_b64 vcc, exec, s[16:17]
	s_cbranch_vccz .LBB0_908
	s_barrier
